# CDIL (dil combine) loop: two trips per pass - 14 loads in flight per lane instead of 7, second copy with renamed temporaries, waits raised accordingly
# speedup vs baseline: 1.0116x; 1.0116x over previous
; __device__ __forceinline__ unsigned pk_bf16(float lo, float hi) { const f32x2 v = {lo, hi}; const bf16v2 b = __builtin_convertvector(v, bf16v2); return __builtin_bit_cast(unsigned, b); }
; __device__ __forceinline__ float bf_lo(unsigned u) { return __uint_as_float(u << 16); }
; __device__ __forceinline__ float bf_hi(unsigned u) { return __uint_as_float(u & 0xffff0000u); }
; __device__ __forceinline__ float silu_f(float v) { return v * __builtin_amdgcn_rcpf(1.0f + __builtin_amdgcn_exp2f(-LOG2E * v)); }
; __device__ __forceinline__ int tid_opaque() { int t = threadIdx.x; asm volatile("" : "+v"(t)); return t; }
; __device__ __forceinline__ void dil_combine_phase(const Params& p, int half) {
;     ...
;     for (int idx = blockIdx.x * 512 + tid_opaque(); idx < 16384 * 128; idx += nth) {
;         const int row = idx >> 7, e = (idx & 127) * 8, h = e >> 7;
;         const float l0 = LSE[(size_t)row * 8 + h], l1 = LSE[(size_t)(16384 + row) * 8 + h], l2 = LSE[(size_t)(32768 + row) * 8 + h];
;         const float mx = fmaxf(l0, fmaxf(l1, l2)); float w0 = __builtin_amdgcn_exp2f(l0 - mx), w1 = __builtin_amdgcn_exp2f(l1 - mx), w2 = __builtin_amdgcn_exp2f(l2 - mx);
;         const float inv = 1.0f / (w0 + w1 + w2); w0 *= inv; w1 *= inv; w2 *= inv;
;         const u32x4 a = *(const u32x4*)(OG + (size_t)row * DM + e), b = *(const u32x4*)(OG + (size_t)(16384 + row) * DM + e), c = *(const u32x4*)(OG + (size_t)(32768 + row) * DM + e);
;         const u32x4 z = *(const u32x4*)(PROJ + (size_t)row * 8192 + 7168 + e);
;         u32x4 o;
; #pragma unroll
;         for (int j = 0; j < 4; ++j) {
;             const float lo = (w0 * bf_lo(a[j]) + w1 * bf_lo(b[j]) + w2 * bf_lo(c[j])) * silu_f(bf_lo(z[j]));
;             const float hi = (w0 * bf_hi(a[j]) + w1 * bf_hi(b[j]) + w2 * bf_hi(c[j])) * silu_f(bf_hi(z[j]));
;             o[j] = pk_bf16(lo, hi);
;         }
;         *(u32x4*)(Y + (size_t)row * DM + e) = o;
.LBB0_68:
	v_ashrrev_i32_e32 v20, 7, v1
	v_ashrrev_i32_e32 v21, 31, v20
	v_lshlrev_b64 v[2:3], 5, v[20:21]
	v_lshrrev_b32_e32 v4, 5, v7
	v_lshl_add_u64 v[2:3], s[58:59], 0, v[2:3]
	v_and_b32_e32 v4, 28, v4
	v_mov_b32_e32 v5, v0
	v_add_u32_e32 v12, 0x4000, v20
	v_lshl_add_u64 v[2:3], v[2:3], 0, v[4:5]
	v_ashrrev_i32_e32 v13, 31, v12
	global_load_dword v6, v[2:3], off
	v_lshlrev_b64 v[2:3], 5, v[12:13]
	v_lshl_add_u64 v[2:3], s[58:59], 0, v[2:3]
	v_add_u32_e32 v16, 0x8000, v20
	v_lshl_add_u64 v[2:3], v[2:3], 0, v[4:5]
	v_ashrrev_i32_e32 v17, 31, v16
	global_load_dword v42, v[2:3], off
	v_lshlrev_b64 v[2:3], 5, v[16:17]
	v_lshl_add_u64 v[2:3], s[58:59], 0, v[2:3]
	v_lshl_add_u64 v[2:3], v[2:3], 0, v[4:5]
	global_load_dword v2, v[2:3], off
	v_and_b32_e32 v10, 0x3f8, v7
	v_lshlrev_b64 v[16:17], 11, v[16:17]
	s_mov_b32 s2, 0xd603000
	v_lshl_add_u64 v[16:17], s[90:91], 0, v[16:17]
	v_lshlrev_b64 v[12:13], 11, v[12:13]
	v_lshl_add_u64 v[12:13], s[90:91], 0, v[12:13]
	v_add_u32_e32 v1, s64, v1
	v_lshlrev_b64 v[36:37], 11, v[20:21]
	v_lshlrev_b64 v[20:21], 14, v[20:21]
	v_lshlrev_b32_e32 v38, 1, v10
	v_mov_b32_e32 v39, v0
	v_lshl_add_u64 v[20:21], s[68:69], 0, v[20:21]
	v_lshl_add_u64 v[20:21], v[20:21], 0, v[38:39]
	v_add_co_u32_e32 v20, vcc, s2, v20
	v_lshl_add_u64 v[8:9], s[90:91], 0, v[36:37]
	v_lshl_add_u64 v[16:17], v[16:17], 0, v[38:39]
	v_addc_co_u32_e32 v21, vcc, 0, v21, vcc
	v_lshl_add_u64 v[8:9], v[8:9], 0, v[38:39]
	global_load_dwordx4 v[16:19], v[16:17], off
	v_lshl_add_u64 v[12:13], v[12:13], 0, v[38:39]
	global_load_dwordx4 v[20:23], v[20:21], off offset:2048
	global_load_dwordx4 v[8:11], v[8:9], off
	global_load_dwordx4 v[12:15], v[12:13], off
	v_add_u32_e32 v7, s73, v7
	v_ashrrev_i32_e32 v68, 7, v1
	v_ashrrev_i32_e32 v69, 31, v68
	v_lshlrev_b64 v[50:51], 5, v[68:69]
	v_lshrrev_b32_e32 v52, 5, v7
	v_lshl_add_u64 v[50:51], s[58:59], 0, v[50:51]
	v_and_b32_e32 v52, 28, v52
	v_mov_b32_e32 v53, v0
	v_add_u32_e32 v60, 0x4000, v68
	v_lshl_add_u64 v[50:51], v[50:51], 0, v[52:53]
	v_ashrrev_i32_e32 v61, 31, v60
	global_load_dword v54, v[50:51], off
	v_lshlrev_b64 v[50:51], 5, v[60:61]
	v_lshl_add_u64 v[50:51], s[58:59], 0, v[50:51]
	v_add_u32_e32 v64, 0x8000, v68
	v_lshl_add_u64 v[50:51], v[50:51], 0, v[52:53]
	v_ashrrev_i32_e32 v65, 31, v64
	global_load_dword v90, v[50:51], off
	v_lshlrev_b64 v[50:51], 5, v[64:65]
	v_lshl_add_u64 v[50:51], s[58:59], 0, v[50:51]
	v_lshl_add_u64 v[50:51], v[50:51], 0, v[52:53]
	global_load_dword v50, v[50:51], off
	v_and_b32_e32 v58, 0x3f8, v7
	v_lshlrev_b64 v[64:65], 11, v[64:65]
	s_mov_b32 s2, 0xd603000
	v_lshl_add_u64 v[64:65], s[90:91], 0, v[64:65]
	v_lshlrev_b64 v[60:61], 11, v[60:61]
	v_lshl_add_u64 v[60:61], s[90:91], 0, v[60:61]
	v_add_u32_e32 v1, s64, v1
	v_lshlrev_b64 v[84:85], 11, v[68:69]
	v_lshlrev_b64 v[68:69], 14, v[68:69]
	v_lshlrev_b32_e32 v86, 1, v58
	v_mov_b32_e32 v87, v0
	v_lshl_add_u64 v[68:69], s[68:69], 0, v[68:69]
	v_lshl_add_u64 v[68:69], v[68:69], 0, v[86:87]
	v_add_co_u32_e32 v68, vcc, s2, v68
	v_lshl_add_u64 v[56:57], s[90:91], 0, v[84:85]
	v_lshl_add_u64 v[64:65], v[64:65], 0, v[86:87]
	v_addc_co_u32_e32 v69, vcc, 0, v69, vcc
	v_lshl_add_u64 v[56:57], v[56:57], 0, v[86:87]
	global_load_dwordx4 v[64:67], v[64:65], off
	v_lshl_add_u64 v[60:61], v[60:61], 0, v[86:87]
	global_load_dwordx4 v[68:71], v[68:69], off offset:2048
	global_load_dwordx4 v[56:59], v[56:57], off
	global_load_dwordx4 v[60:63], v[60:61], off
	v_add_u32_e32 v7, s73, v7
	s_waitcnt vmcnt(11)
	v_max3_f32 v3, v6, v42, v2
	v_sub_f32_e32 v4, v6, v3
	v_exp_f32_e32 v25, v4
	v_sub_f32_e32 v4, v42, v3
	v_exp_f32_e32 v24, v4
	v_sub_f32_e32 v2, v2, v3
	v_exp_f32_e32 v2, v2
	v_add_f32_e32 v3, v25, v24
	v_add_f32_e32 v3, v2, v3
	v_div_scale_f32 v4, s[4:5], v3, v3, 1.0
	v_rcp_f32_e32 v5, v4
	s_nop 0
	v_fma_f32 v6, -v4, v5, 1.0
	v_fmac_f32_e32 v5, v6, v5
	v_div_scale_f32 v6, vcc, 1.0, v3, 1.0
	v_mul_f32_e32 v42, v6, v5
	v_fma_f32 v43, -v4, v42, v6
	v_fmac_f32_e32 v42, v43, v5
	v_fma_f32 v4, -v4, v42, v6
	v_div_fmas_f32 v4, v4, v5, v42
	v_div_fixup_f32 v26, v4, v3, 1.0
	v_mul_f32_e32 v6, v2, v26
	v_pk_mul_f32 v[24:25], v[24:25], v[26:27] op_sel_hi:[1,0]
	s_mov_b32 s2, 0x1fffff
	v_lshl_add_u64 v[2:3], s[40:41], 0, v[36:37]
	v_cmp_lt_i32_e32 vcc, s2, v1
	v_lshl_add_u64 v[2:3], v[2:3], 0, v[38:39]
	s_or_b64 s[42:43], vcc, s[42:43]
	s_waitcnt vmcnt(10)
	v_lshlrev_b32_e32 v34, 16, v16
	v_and_b32_e32 v35, 0xffff0000, v16
	s_waitcnt vmcnt(9)
	v_lshlrev_b32_e32 v26, 16, v20
	v_and_b32_e32 v27, 0xffff0000, v20
	v_mul_f32_e32 v20, 0xbfb8aa3b, v26
	s_waitcnt vmcnt(8)
	v_and_b32_e32 v31, 0xffff0000, v8
	v_lshlrev_b32_e32 v32, 16, v8
	v_mul_f32_e32 v8, 0xbfb8aa3b, v27
	v_exp_f32_e32 v20, v20
	v_exp_f32_e32 v8, v8
	s_waitcnt vmcnt(7)
; __device__ __forceinline__ unsigned pk_bf16(float lo, float hi) { const f32x2 v = {lo, hi}; const bf16v2 b = __builtin_convertvector(v, bf16v2); return __builtin_bit_cast(unsigned, b); }
; __device__ __forceinline__ float bf_lo(unsigned u) { return __uint_as_float(u << 16); }
; __device__ __forceinline__ float bf_hi(unsigned u) { return __uint_as_float(u & 0xffff0000u); }
; __device__ __forceinline__ float silu_f(float v) { return v * __builtin_amdgcn_rcpf(1.0f + __builtin_amdgcn_exp2f(-LOG2E * v)); }
; __device__ __forceinline__ int tid_opaque() { int t = threadIdx.x; asm volatile("" : "+v"(t)); return t; }
; __device__ __forceinline__ void dil_combine_phase(const Params& p, int half) {
;     ...
;     for (int idx = blockIdx.x * 512 + tid_opaque(); idx < 16384 * 128; idx += nth) {
;         const int row = idx >> 7, e = (idx & 127) * 8, h = e >> 7;
;         const float l0 = LSE[(size_t)row * 8 + h], l1 = LSE[(size_t)(16384 + row) * 8 + h], l2 = LSE[(size_t)(32768 + row) * 8 + h];
;         const float mx = fmaxf(l0, fmaxf(l1, l2)); float w0 = __builtin_amdgcn_exp2f(l0 - mx), w1 = __builtin_amdgcn_exp2f(l1 - mx), w2 = __builtin_amdgcn_exp2f(l2 - mx);
;         const float inv = 1.0f / (w0 + w1 + w2); w0 *= inv; w1 *= inv; w2 *= inv;
;         const u32x4 a = *(const u32x4*)(OG + (size_t)row * DM + e), b = *(const u32x4*)(OG + (size_t)(16384 + row) * DM + e), c = *(const u32x4*)(OG + (size_t)(32768 + row) * DM + e);
;         const u32x4 z = *(const u32x4*)(PROJ + (size_t)row * 8192 + 7168 + e);
;         u32x4 o;
; #pragma unroll
;         for (int j = 0; j < 4; ++j) {
;             const float lo = (w0 * bf_lo(a[j]) + w1 * bf_lo(b[j]) + w2 * bf_lo(c[j])) * silu_f(bf_lo(z[j]));
;             const float hi = (w0 * bf_hi(a[j]) + w1 * bf_hi(b[j]) + w2 * bf_hi(c[j])) * silu_f(bf_hi(z[j]));
;             o[j] = pk_bf16(lo, hi);
;         }
;         *(u32x4*)(Y + (size_t)row * DM + e) = o;
	v_and_b32_e32 v33, 0xffff0000, v12
	v_lshlrev_b32_e32 v30, 16, v12
	v_add_f32_e32 v20, 1.0, v20
	v_add_f32_e32 v8, 1.0, v8
	v_rcp_f32_e32 v28, v20
	v_rcp_f32_e32 v29, v8
	v_lshlrev_b32_e32 v20, 16, v21
	v_and_b32_e32 v21, 0xffff0000, v21
	v_mul_f32_e32 v12, 0xbfb8aa3b, v20
	v_pk_mul_f32 v[26:27], v[28:29], v[26:27]
	v_pk_mul_f32 v[28:29], v[24:25], v[32:33] op_sel:[1,0] op_sel_hi:[0,1]
	v_pk_fma_f32 v[28:29], v[24:25], v[30:31], v[28:29]
	v_exp_f32_e32 v12, v12
	v_pk_fma_f32 v[28:29], v[6:7], v[34:35], v[28:29] op_sel_hi:[0,1,1]
	v_pk_mul_f32 v[26:27], v[28:29], v[26:27]
	v_lshlrev_b32_e32 v28, 16, v9
	v_cvt_pk_bf16_f32 v8, v26, v27
	v_and_b32_e32 v27, 0xffff0000, v9
	v_mul_f32_e32 v9, 0xbfb8aa3b, v21
	v_exp_f32_e32 v9, v9
	v_add_f32_e32 v12, 1.0, v12
	v_rcp_f32_e32 v12, v12
	v_lshlrev_b32_e32 v26, 16, v13
	v_add_f32_e32 v9, 1.0, v9
	v_and_b32_e32 v29, 0xffff0000, v13
	v_rcp_f32_e32 v13, v9
	v_lshlrev_b32_e32 v16, 16, v17
	v_and_b32_e32 v17, 0xffff0000, v17
	v_pk_mul_f32 v[12:13], v[12:13], v[20:21]
	v_pk_mul_f32 v[20:21], v[24:25], v[28:29] op_sel:[1,0] op_sel_hi:[0,1]
	v_pk_fma_f32 v[20:21], v[24:25], v[26:27], v[20:21]
	v_lshlrev_b32_e32 v26, 16, v10
	v_pk_fma_f32 v[16:17], v[6:7], v[16:17], v[20:21] op_sel_hi:[0,1,1]
	v_pk_mul_f32 v[12:13], v[16:17], v[12:13]
	v_and_b32_e32 v21, 0xffff0000, v10
	v_cvt_pk_bf16_f32 v9, v12, v13
	v_lshlrev_b32_e32 v12, 16, v22
	v_and_b32_e32 v13, 0xffff0000, v22
	v_mul_f32_e32 v16, 0xbfb8aa3b, v12
	v_mul_f32_e32 v10, 0xbfb8aa3b, v13
	v_exp_f32_e32 v16, v16
	v_exp_f32_e32 v10, v10
	v_and_b32_e32 v27, 0xffff0000, v14
	v_lshlrev_b32_e32 v20, 16, v14
	v_add_f32_e32 v16, 1.0, v16
	v_add_f32_e32 v10, 1.0, v10
	v_rcp_f32_e32 v16, v16
	v_rcp_f32_e32 v17, v10
	v_lshlrev_b32_e32 v28, 16, v18
	v_and_b32_e32 v29, 0xffff0000, v18
	v_lshlrev_b32_e32 v18, 16, v19
	v_pk_mul_f32 v[12:13], v[16:17], v[12:13]
	v_pk_mul_f32 v[16:17], v[24:25], v[26:27] op_sel:[1,0] op_sel_hi:[0,1]
	v_pk_fma_f32 v[16:17], v[24:25], v[20:21], v[16:17]
	v_lshlrev_b32_e32 v20, 16, v11
	v_pk_fma_f32 v[16:17], v[6:7], v[28:29], v[16:17] op_sel_hi:[0,1,1]
	v_and_b32_e32 v21, 0xffff0000, v15
	v_pk_mul_f32 v[12:13], v[16:17], v[12:13]
	v_lshlrev_b32_e32 v16, 16, v15
	v_and_b32_e32 v17, 0xffff0000, v11
	v_pk_mul_f32 v[20:21], v[24:25], v[20:21] op_sel:[1,0] op_sel_hi:[0,1]
	v_cvt_pk_bf16_f32 v10, v12, v13
	v_lshlrev_b32_e32 v12, 16, v23
	v_and_b32_e32 v13, 0xffff0000, v23
	v_pk_fma_f32 v[16:17], v[24:25], v[16:17], v[20:21]
	v_and_b32_e32 v19, 0xffff0000, v19
	v_mul_f32_e32 v14, 0xbfb8aa3b, v12
	v_pk_fma_f32 v[16:17], v[6:7], v[18:19], v[16:17] op_sel_hi:[0,1,1]
	v_mul_f32_e32 v6, 0xbfb8aa3b, v13
	v_exp_f32_e32 v14, v14
	v_exp_f32_e32 v6, v6
	v_add_f32_e32 v14, 1.0, v14
	v_add_f32_e32 v6, 1.0, v6
	v_rcp_f32_e32 v14, v14
	v_rcp_f32_e32 v15, v6
	s_nop 0
	v_pk_mul_f32 v[12:13], v[14:15], v[12:13]
	s_nop 0
	v_pk_mul_f32 v[12:13], v[16:17], v[12:13]
	s_nop 0
	v_cvt_pk_bf16_f32 v11, v12, v13
	global_store_dwordx4 v[2:3], v[8:11], off
	s_waitcnt vmcnt(5)
	v_max3_f32 v51, v54, v90, v50
	v_sub_f32_e32 v52, v54, v51
	v_exp_f32_e32 v73, v52
	v_sub_f32_e32 v52, v90, v51
	v_exp_f32_e32 v72, v52
	v_sub_f32_e32 v50, v50, v51
	v_exp_f32_e32 v50, v50
	v_add_f32_e32 v51, v73, v72
	v_add_f32_e32 v51, v50, v51
	v_div_scale_f32 v52, s[4:5], v51, v51, 1.0
	v_rcp_f32_e32 v53, v52
	s_nop 0
	v_fma_f32 v54, -v52, v53, 1.0
	v_fmac_f32_e32 v53, v54, v53
	v_div_scale_f32 v54, vcc, 1.0, v51, 1.0
	v_mul_f32_e32 v90, v54, v53
	v_fma_f32 v91, -v52, v90, v54
	v_fmac_f32_e32 v90, v91, v53
	v_fma_f32 v52, -v52, v90, v54
	v_div_fmas_f32 v52, v52, v53, v90
	v_div_fixup_f32 v74, v52, v51, 1.0
	v_mul_f32_e32 v54, v50, v74
	v_pk_mul_f32 v[72:73], v[72:73], v[74:75] op_sel_hi:[1,0]
	s_mov_b32 s2, 0x1fffff
	v_lshl_add_u64 v[50:51], s[40:41], 0, v[84:85]
	v_cmp_lt_i32_e32 vcc, s2, v1
	v_lshl_add_u64 v[50:51], v[50:51], 0, v[86:87]
	s_or_b64 s[42:43], vcc, s[42:43]
	s_waitcnt vmcnt(4)
; __device__ __forceinline__ unsigned pk_bf16(float lo, float hi) { const f32x2 v = {lo, hi}; const bf16v2 b = __builtin_convertvector(v, bf16v2); return __builtin_bit_cast(unsigned, b); }
; __device__ __forceinline__ float bf_lo(unsigned u) { return __uint_as_float(u << 16); }
; __device__ __forceinline__ float bf_hi(unsigned u) { return __uint_as_float(u & 0xffff0000u); }
; __device__ __forceinline__ float silu_f(float v) { return v * __builtin_amdgcn_rcpf(1.0f + __builtin_amdgcn_exp2f(-LOG2E * v)); }
; __device__ __forceinline__ int tid_opaque() { int t = threadIdx.x; asm volatile("" : "+v"(t)); return t; }
; __device__ __forceinline__ void dil_combine_phase(const Params& p, int half) {
;     ...
;     for (int idx = blockIdx.x * 512 + tid_opaque(); idx < 16384 * 128; idx += nth) {
;         const int row = idx >> 7, e = (idx & 127) * 8, h = e >> 7;
;         const float l0 = LSE[(size_t)row * 8 + h], l1 = LSE[(size_t)(16384 + row) * 8 + h], l2 = LSE[(size_t)(32768 + row) * 8 + h];
;         const float mx = fmaxf(l0, fmaxf(l1, l2)); float w0 = __builtin_amdgcn_exp2f(l0 - mx), w1 = __builtin_amdgcn_exp2f(l1 - mx), w2 = __builtin_amdgcn_exp2f(l2 - mx);
;         const float inv = 1.0f / (w0 + w1 + w2); w0 *= inv; w1 *= inv; w2 *= inv;
;         const u32x4 a = *(const u32x4*)(OG + (size_t)row * DM + e), b = *(const u32x4*)(OG + (size_t)(16384 + row) * DM + e), c = *(const u32x4*)(OG + (size_t)(32768 + row) * DM + e);
;         const u32x4 z = *(const u32x4*)(PROJ + (size_t)row * 8192 + 7168 + e);
;         u32x4 o;
; #pragma unroll
;         for (int j = 0; j < 4; ++j) {
;             const float lo = (w0 * bf_lo(a[j]) + w1 * bf_lo(b[j]) + w2 * bf_lo(c[j])) * silu_f(bf_lo(z[j]));
;             const float hi = (w0 * bf_hi(a[j]) + w1 * bf_hi(b[j]) + w2 * bf_hi(c[j])) * silu_f(bf_hi(z[j]));
;             o[j] = pk_bf16(lo, hi);
;         }
;         *(u32x4*)(Y + (size_t)row * DM + e) = o;
	v_lshlrev_b32_e32 v82, 16, v64
	v_and_b32_e32 v83, 0xffff0000, v64
	s_waitcnt vmcnt(3)
	v_lshlrev_b32_e32 v74, 16, v68
	v_and_b32_e32 v75, 0xffff0000, v68
	v_mul_f32_e32 v68, 0xbfb8aa3b, v74
	s_waitcnt vmcnt(2)
	v_and_b32_e32 v79, 0xffff0000, v56
	v_lshlrev_b32_e32 v80, 16, v56
	v_mul_f32_e32 v56, 0xbfb8aa3b, v75
	v_exp_f32_e32 v68, v68
	v_exp_f32_e32 v56, v56
	s_waitcnt vmcnt(1)
	v_and_b32_e32 v81, 0xffff0000, v60
	v_lshlrev_b32_e32 v78, 16, v60
	v_add_f32_e32 v68, 1.0, v68
	v_add_f32_e32 v56, 1.0, v56
	v_rcp_f32_e32 v76, v68
	v_rcp_f32_e32 v77, v56
	v_lshlrev_b32_e32 v68, 16, v69
	v_and_b32_e32 v69, 0xffff0000, v69
	v_mul_f32_e32 v60, 0xbfb8aa3b, v68
	v_pk_mul_f32 v[74:75], v[76:77], v[74:75]
	v_pk_mul_f32 v[76:77], v[72:73], v[80:81] op_sel:[1,0] op_sel_hi:[0,1]
	v_pk_fma_f32 v[76:77], v[72:73], v[78:79], v[76:77]
	v_exp_f32_e32 v60, v60
	v_pk_fma_f32 v[76:77], v[54:55], v[82:83], v[76:77] op_sel_hi:[0,1,1]
	v_pk_mul_f32 v[74:75], v[76:77], v[74:75]
	v_lshlrev_b32_e32 v76, 16, v57
	v_cvt_pk_bf16_f32 v56, v74, v75
	v_and_b32_e32 v75, 0xffff0000, v57
	v_mul_f32_e32 v57, 0xbfb8aa3b, v69
	v_exp_f32_e32 v57, v57
	v_add_f32_e32 v60, 1.0, v60
	v_rcp_f32_e32 v60, v60
	v_lshlrev_b32_e32 v74, 16, v61
	v_add_f32_e32 v57, 1.0, v57
	v_and_b32_e32 v77, 0xffff0000, v61
	v_rcp_f32_e32 v61, v57
	v_lshlrev_b32_e32 v64, 16, v65
	v_and_b32_e32 v65, 0xffff0000, v65
	v_pk_mul_f32 v[60:61], v[60:61], v[68:69]
	v_pk_mul_f32 v[68:69], v[72:73], v[76:77] op_sel:[1,0] op_sel_hi:[0,1]
	v_pk_fma_f32 v[68:69], v[72:73], v[74:75], v[68:69]
	v_lshlrev_b32_e32 v74, 16, v58
	v_pk_fma_f32 v[64:65], v[54:55], v[64:65], v[68:69] op_sel_hi:[0,1,1]
	v_pk_mul_f32 v[60:61], v[64:65], v[60:61]
	v_and_b32_e32 v69, 0xffff0000, v58
	v_cvt_pk_bf16_f32 v57, v60, v61
	v_lshlrev_b32_e32 v60, 16, v70
	v_and_b32_e32 v61, 0xffff0000, v70
	v_mul_f32_e32 v64, 0xbfb8aa3b, v60
	v_mul_f32_e32 v58, 0xbfb8aa3b, v61
	v_exp_f32_e32 v64, v64
	v_exp_f32_e32 v58, v58
	v_and_b32_e32 v75, 0xffff0000, v62
	v_lshlrev_b32_e32 v68, 16, v62
	v_add_f32_e32 v64, 1.0, v64
	v_add_f32_e32 v58, 1.0, v58
	v_rcp_f32_e32 v64, v64
	v_rcp_f32_e32 v65, v58
	v_lshlrev_b32_e32 v76, 16, v66
	v_and_b32_e32 v77, 0xffff0000, v66
	v_lshlrev_b32_e32 v66, 16, v67
	v_pk_mul_f32 v[60:61], v[64:65], v[60:61]
	v_pk_mul_f32 v[64:65], v[72:73], v[74:75] op_sel:[1,0] op_sel_hi:[0,1]
	v_pk_fma_f32 v[64:65], v[72:73], v[68:69], v[64:65]
	v_lshlrev_b32_e32 v68, 16, v59
	v_pk_fma_f32 v[64:65], v[54:55], v[76:77], v[64:65] op_sel_hi:[0,1,1]
	v_and_b32_e32 v69, 0xffff0000, v63
	v_pk_mul_f32 v[60:61], v[64:65], v[60:61]
	v_lshlrev_b32_e32 v64, 16, v63
	v_and_b32_e32 v65, 0xffff0000, v59
	v_pk_mul_f32 v[68:69], v[72:73], v[68:69] op_sel:[1,0] op_sel_hi:[0,1]
	v_cvt_pk_bf16_f32 v58, v60, v61
	v_lshlrev_b32_e32 v60, 16, v71
	v_and_b32_e32 v61, 0xffff0000, v71
	v_pk_fma_f32 v[64:65], v[72:73], v[64:65], v[68:69]
	v_and_b32_e32 v67, 0xffff0000, v67
	v_mul_f32_e32 v62, 0xbfb8aa3b, v60
	v_pk_fma_f32 v[64:65], v[54:55], v[66:67], v[64:65] op_sel_hi:[0,1,1]
	v_mul_f32_e32 v54, 0xbfb8aa3b, v61
	v_exp_f32_e32 v62, v62
	v_exp_f32_e32 v54, v54
	v_add_f32_e32 v62, 1.0, v62
	v_add_f32_e32 v54, 1.0, v54
	v_rcp_f32_e32 v62, v62
	v_rcp_f32_e32 v63, v54
	s_nop 0
	v_pk_mul_f32 v[60:61], v[62:63], v[60:61]
	s_nop 0
	v_pk_mul_f32 v[60:61], v[64:65], v[60:61]
	s_nop 0
	v_cvt_pk_bf16_f32 v59, v60, v61
	global_store_dwordx4 v[50:51], v[56:59], off
	s_andn2_b64 exec, exec, s[42:43]
	s_cbranch_execnz .LBB0_68
